# v3
# speedup vs baseline: 1.0084x; 1.0030x over previous
; __device__ __forceinline__ void finishSM(f32x16& p0, f32x16& p1, float alpha, float& l_reg, bf16x8& pa0, bf16x8& pa1, bf16x8& pa2, bf16x8& pa3) {
; #pragma unroll
;   for (int r = 0; r < 16; ++r) p1[r] = __builtin_amdgcn_exp2f(p1[r]);
;   float ps = 0;
; #pragma unroll
;   for (int r = 0; r < 16; ++r) ps += p0[r];
; #pragma unroll
;   for (int r = 0; r < 16; ++r) ps += p1[r];
;   { auto rr = __builtin_amdgcn_permlane32_swap(__float_as_uint(ps), __float_as_uint(ps), false, false);
;     ps = __uint_as_float(rr[0]) + __uint_as_float(rr[1]); }
;   l_reg = l_reg * alpha + ps;
;     ...
;   PK4(p0, 0, pa0); PK4(p0, 8, pa1); PK4(p1, 0, pa2); PK4(p1, 8, pa3);
; __device__ __forceinline__ void qkt(f32x16& p0, f32x16& p1, const char* Ks, const char* Krs, const bf16x8* qr, const char* Qrs, int r32, int hi) {
;   p0 = f32x16{}; p1 = f32x16{};
; #pragma unroll
;   for (int d0 = 0; d0 < 8; ++d0) { const int cb = (d0 * 16 + hi * 8) * 2;
;     const bf16x8 b0 = *reinterpret_cast<const bf16x8*>(Ks + KSWZ(r32, cb));
;     const bf16x8 b1 = *reinterpret_cast<const bf16x8*>(Ks + KSWZ(32 + r32, cb));
;     p0 = __builtin_amdgcn_mfma_f32_32x32x16_bf16(b0, qr[d0], p0, 0, 0, 0);
;     p1 = __builtin_amdgcn_mfma_f32_32x32x16_bf16(b1, qr[d0], p1, 0, 0, 0); }
; #pragma unroll
;   for (int d0 = 0; d0 < 4; ++d0) { const int slot = d0 * 2 + hi;
;     const bf16x8 b0 = *reinterpret_cast<const bf16x8*>(Krs + RSWZ(r32, slot));
;     const bf16x8 b1 = *reinterpret_cast<const bf16x8*>(Krs + RSWZ(32 + r32, slot));
;     const bf16x8 qf = *reinterpret_cast<const bf16x8*>(Qrs + RSWZ(r32, slot));
;     p0 = __builtin_amdgcn_mfma_f32_32x32x16_bf16(b0, qf, p0, 0, 0, 0);
;     p1 = __builtin_amdgcn_mfma_f32_32x32x16_bf16(b1, qf, p1, 0, 0, 0); }
; }
.LBB0_353:
	s_add_u32 s46, s70, 0x20000
	s_addc_u32 s47, s71, 0
	ds_read_b128 v[64:67], v169 offset:49152
	ds_read_b128 v[68:71], v169 offset:57344
	ds_read_b128 v[196:199], v170 offset:49152
	ds_read_b128 v[204:207], v170 offset:57344
	ds_read_b128 v[238:241], v171 offset:49152
	ds_read_b128 v[242:245], v171 offset:57344
	v_or_b32_e32 v164, 0x12000, v181
	v_or_b32_e32 v165, 0x13000, v181
	v_add_u32_e32 v168, v155, v181
	v_or_b32_e32 v167, 0x12000, v184
	v_add_u32_e32 v187, v155, v184
	v_exp_f32_e32 v158, v134
	v_add_f32_e32 v134, 0, v213
	s_add_u32 m0, s98, 0x8000
	s_waitcnt lgkmcnt(5)
	v_mfma_f32_32x32x16_bf16 v[80:95], v[64:67], v[124:127], 0
	global_load_lds_dwordx4 v130, s[70:71]
	v_add_f32_e32 v134, v217, v134
	v_add_f32_e32 v134, v218, v134
	v_add_f32_e32 v134, v220, v134
	v_add_f32_e32 v134, v221, v134
	v_add_f32_e32 v134, v223, v134
	v_add_f32_e32 v134, v222, v134
	v_add_f32_e32 v134, v224, v134
	s_add_u32 m0, s98, 0xa000
	s_waitcnt lgkmcnt(4)
	v_mfma_f32_32x32x16_bf16 v[64:79], v[68:71], v[124:127], 0
	global_load_lds_dwordx4 v130, s[46:47]
	v_add_f32_e32 v134, v209, v134
	v_add_f32_e32 v134, v210, v134
	v_add_f32_e32 v134, v211, v134
	v_add_f32_e32 v134, v214, v134
	v_exp_f32_e32 v146, v146
	v_add_f32_e32 v134, v212, v134
	v_exp_f32_e32 v147, v147
	s_add_u32 m0, s98, 0x10000
	s_waitcnt lgkmcnt(3)
	v_mfma_f32_32x32x16_bf16 v[80:95], v[196:199], v[120:123], v[80:95]
	global_load_lds_dwordx4 v132, s[72:73]
	v_add_f32_e32 v134, v215, v134
	v_exp_f32_e32 v144, v144
	v_add_f32_e32 v134, v216, v134
	v_exp_f32_e32 v145, v145
	v_add_f32_e32 v134, v219, v134
	v_or_b32_e32 v203, 0x13000, v184
	v_exp_f32_e32 v150, v140
	s_add_u32 m0, s98, 0x4000
	s_waitcnt lgkmcnt(2)
	v_mfma_f32_32x32x16_bf16 v[64:79], v[204:207], v[120:123], v[64:79]
	global_load_lds_dwordx4 v131, s[70:71]
	ds_read_b128 v[196:199], v172 offset:49152
	ds_read_b128 v[204:207], v172 offset:57344
	v_add_f32_e32 v134, v146, v134
	v_exp_f32_e32 v151, v141
	v_add_f32_e32 v134, v147, v134
	v_exp_f32_e32 v156, v136
	v_add_f32_e32 v134, v144, v134
	v_exp_f32_e32 v157, v137
	s_add_u32 m0, s98, 0x6000
	s_waitcnt lgkmcnt(3)
	v_mfma_f32_32x32x16_bf16 v[80:95], v[238:241], v[116:119], v[80:95]
	global_load_lds_dwordx4 v131, s[46:47]
	s_add_u32 s70, s70, 0x40000
	s_addc_u32 s71, s71, 0
	s_add_u32 s72, s72, 0x2000
	s_addc_u32 s73, s73, 0
	v_add_f32_e32 v134, v145, v134
	v_add_f32_e32 v134, v150, v134
	v_exp_f32_e32 v159, v135
	v_add_f32_e32 v134, v151, v134
	v_exp_f32_e32 v148, v148
	v_add_f32_e32 v134, v156, v134
	v_exp_f32_e32 v149, v149
	s_waitcnt lgkmcnt(2)
	v_mfma_f32_32x32x16_bf16 v[64:79], v[242:245], v[116:119], v[64:79]
	ds_read_b128 v[238:241], v173 offset:49152
	ds_read_b128 v[242:245], v173 offset:57344
	v_add_f32_e32 v134, v157, v134
	v_add_f32_e32 v134, v158, v134
	v_exp_f32_e32 v208, v143
	v_add_f32_e32 v134, v159, v134
	v_exp_f32_e32 v225, v138
	v_add_f32_e32 v134, v148, v134
	s_waitcnt lgkmcnt(3)
	v_mfma_f32_32x32x16_bf16 v[80:95], v[196:199], v[112:115], v[80:95]
	v_add_f32_e32 v134, v149, v134
	v_cvt_pk_bf16_f32 v136, v221, v223
	v_cvt_pk_bf16_f32 v135, v218, v220
	v_cvt_pk_bf16_f32 v137, v222, v224
	v_cvt_pk_bf16_f32 v138, v209, v210
	v_cvt_pk_bf16_f32 v140, v212, v215
	v_cvt_pk_bf16_f32 v141, v216, v219
	s_waitcnt lgkmcnt(2)
	v_mfma_f32_32x32x16_bf16 v[64:79], v[204:207], v[112:115], v[64:79]
	ds_read_b128 v[196:199], v174 offset:49152
	ds_read_b128 v[204:207], v174 offset:57344
	v_cvt_pk_bf16_f32 v143, v144, v145
	v_cvt_pk_bf16_f32 v144, v150, v151
	v_cvt_pk_bf16_f32 v145, v156, v157
	v_permlane32_swap_b32_e32 v135, v137
	v_permlane32_swap_b32_e32 v138, v140
	s_waitcnt lgkmcnt(3)
	v_mfma_f32_32x32x16_bf16 v[80:95], v[238:241], v[108:111], v[80:95]
	v_permlane32_swap_b32_e32 v143, v145
	s_waitcnt lgkmcnt(2)
	v_mfma_f32_32x32x16_bf16 v[64:79], v[242:245], v[108:111], v[64:79]
	ds_read_b128 v[238:241], v175 offset:49152
	ds_read_b128 v[242:245], v175 offset:57344
	s_waitcnt lgkmcnt(3)
	v_mfma_f32_32x32x16_bf16 v[80:95], v[196:199], v[104:107], v[80:95]
	s_waitcnt lgkmcnt(2)
	v_mfma_f32_32x32x16_bf16 v[64:79], v[204:207], v[104:107], v[64:79]
	ds_read_b128 v[196:199], v176 offset:49152
	ds_read_b128 v[204:207], v176 offset:57344
	s_waitcnt lgkmcnt(3)
	v_mfma_f32_32x32x16_bf16 v[80:95], v[238:241], v[100:103], v[80:95]
	s_waitcnt lgkmcnt(2)
	v_mfma_f32_32x32x16_bf16 v[64:79], v[242:245], v[100:103], v[64:79]
	ds_read_b128 v[238:241], v193
	ds_read_b128 v[242:245], v194
	ds_read_b128 v[246:249], v192
	s_waitcnt lgkmcnt(4)
	v_mfma_f32_32x32x16_bf16 v[80:95], v[196:199], v[96:99], v[80:95]
	s_waitcnt lgkmcnt(3)
	v_mfma_f32_32x32x16_bf16 v[64:79], v[204:207], v[96:99], v[64:79]
	ds_read_b128 v[196:199], v189
	ds_read_b128 v[204:207], v190
	ds_read_b128 v[226:229], v191
	s_waitcnt lgkmcnt(3)
	v_mfma_f32_32x32x16_bf16 v[80:95], v[238:241], v[246:249], v[80:95]
	s_waitcnt lgkmcnt(3)
	v_mfma_f32_32x32x16_bf16 v[64:79], v[242:245], v[246:249], v[64:79]
	ds_read_b128 v[238:241], v164
	ds_read_b128 v[242:245], v165
	ds_read_b128 v[246:249], v168
	s_waitcnt lgkmcnt(3)
	v_mfma_f32_32x32x16_bf16 v[80:95], v[196:199], v[226:229], v[80:95]
	s_waitcnt lgkmcnt(3)
	v_mfma_f32_32x32x16_bf16 v[64:79], v[204:207], v[226:229], v[64:79]
	ds_read_b128 v[196:199], v167
	ds_read_b128 v[230:233], v203
	ds_read_b128 v[234:237], v187
	s_waitcnt lgkmcnt(3)
	v_mfma_f32_32x32x16_bf16 v[80:95], v[238:241], v[246:249], v[80:95]
	v_exp_f32_e32 v207, v142
	v_cvt_pk_bf16_f32 v142, v146, v147
	v_cvt_pk_bf16_f32 v146, v158, v159
	v_cvt_pk_bf16_f32 v147, v148, v149
	v_add_f32_e32 v134, v207, v134
	s_waitcnt lgkmcnt(3)
; #define SBAR() __builtin_amdgcn_sched_barrier(0)
; __device__ __forceinline__ void partialSM(f32x16& p0, f32x16& p1, float& m_reg, float& mn, float& alpha) {
;   constexpr float C = ATT_SCALE * 1.4426950408889634f;
;   float pmax = p0[0];
; #pragma unroll
;   for (int r = 1; r < 16; ++r) pmax = fmaxf(pmax, p0[r]);
; #pragma unroll
;   for (int r = 0; r < 16; ++r) pmax = fmaxf(pmax, p1[r]);
;   { auto rr = __builtin_amdgcn_permlane32_swap(__float_as_uint(pmax), __float_as_uint(pmax), false, false);
;     pmax = fmaxf(__uint_as_float(rr[0]), __uint_as_float(rr[1])); }
;   if (__builtin_expect(__all(pmax - m_reg <= ATT_THR / ATT_SCALE), 1)) { mn = m_reg; alpha = 1.f; }
;   else { mn = fmaxf(m_reg, pmax); alpha = __builtin_amdgcn_exp2f((m_reg - mn) * C); m_reg = mn; }
;   const float mnC = -mn * C;
; #pragma unroll
;   for (int r = 0; r < 16; ++r) p0[r] = fmaf(p0[r], C, mnC);
; #pragma unroll
;   for (int r = 0; r < 16; ++r) p1[r] = fmaf(p1[r], C, mnC);
; #pragma unroll
;   for (int r = 0; r < 16; ++r) p0[r] = __builtin_amdgcn_exp2f(p0[r]);
; template <int D0> __device__ __forceinline__ void pv_one(f32x16& od, int vb, bf16x8 pa0, bf16x8 pa1, bf16x8 pa2, bf16x8 pa3) {
;   const s16x4 l0 = tr_read<v_rd_off(D0, 0, 0)>(vb), h0 = tr_read<v_rd_off(D0, 0, 1)>(vb), l1 = tr_read<v_rd_off(D0, 1, 0)>(vb), h1 = tr_read<v_rd_off(D0, 1, 1)>(vb);
;   const s16x4 l2 = tr_read<v_rd_off(D0, 2, 0)>(vb), h2 = tr_read<v_rd_off(D0, 2, 1)>(vb), l3 = tr_read<v_rd_off(D0, 3, 0)>(vb), h3 = tr_read<v_rd_off(D0, 3, 1)>(vb);
;   asm volatile("s_waitcnt lgkmcnt(0)" ::: "memory"); SBAR();
;     ...
;   od = __builtin_amdgcn_mfma_f32_32x32x16_bf16(pa0, PK(l0, h0), od, 0, 0, 0);
;   od = __builtin_amdgcn_mfma_f32_32x32x16_bf16(pa1, PK(l1, h1), od, 0, 0, 0);
;   od = __builtin_amdgcn_mfma_f32_32x32x16_bf16(pa2, PK(l2, h2), od, 0, 0, 0);
;   od = __builtin_amdgcn_mfma_f32_32x32x16_bf16(pa3, PK(l3, h3), od, 0, 0, 0);
;     ...
; }
; __device__ __forceinline__ void pv_d0(f32x16* o, int vb, bf16x8 pa0, bf16x8 pa1, bf16x8 pa2, bf16x8 pa3) {
;   pv_one<0>(o[0], vb, pa0, pa1, pa2, pa3); pv_one<1>(o[1], vb, pa0, pa1, pa2, pa3); pv_one<2>(o[2], vb, pa0, pa1, pa2, pa3); pv_one<3>(o[3], vb, pa0, pa1, pa2, pa3);
	v_mfma_f32_32x32x16_bf16 v[64:79], v[242:245], v[246:249], v[64:79]
	v_add_f32_e32 v134, v208, v134
	v_add_f32_e32 v134, v225, v134
	v_cvt_pk_bf16_f32 v148, v207, v208
	v_permlane32_swap_b32_e32 v142, v144
	s_waitcnt lgkmcnt(0)
	v_mfma_f32_32x32x16_bf16 v[80:95], v[196:199], v[234:237], v[80:95]
	v_exp_f32_e32 v226, v139
	v_cvt_pk_bf16_f32 v139, v211, v214
	s_nop 1
	v_permlane32_swap_b32_e32 v139, v141
	v_add_f32_e32 v205, v226, v134
	v_mov_b32_e32 v206, v205
	v_cvt_pk_bf16_f32 v134, v213, v217
	s_waitcnt lgkmcnt(0)
	v_mfma_f32_32x32x16_bf16 v[64:79], v[230:233], v[234:237], v[64:79]
	v_permlane32_swap_b32_e32 v205, v206
	v_permlane32_swap_b32_e32 v134, v136
	v_cvt_pk_bf16_f32 v149, v225, v226
	v_permlane32_swap_b32_e32 v146, v148
	s_nop 0
	v_permlane32_swap_b32_e32 v147, v149
	ds_read_b64_tr_b16 v[230:231], v163 offset:0
	ds_read_b64_tr_b16 v[232:233], v163 offset:0x800
	ds_read_b64_tr_b16 v[234:235], v163 offset:0x1000
	ds_read_b64_tr_b16 v[236:237], v163 offset:0x1800
	ds_read_b64_tr_b16 v[238:239], v163 offset:0x2000
	ds_read_b64_tr_b16 v[240:241], v163 offset:0x2800
	ds_read_b64_tr_b16 v[242:243], v163 offset:0x3000
	ds_read_b64_tr_b16 v[244:245], v163 offset:0x3800
	s_waitcnt lgkmcnt(0)
	s_nop 0
	v_mfma_f32_32x32x16_bf16 v[48:63], v[134:137], v[230:233], v[48:63]
	ds_read_b64_tr_b16 v[230:231], v163 offset:0x200
	ds_read_b64_tr_b16 v[232:233], v163 offset:0xa00
	v_max_f32_e32 v164, v81, v81
	v_max_f32_e32 v165, v80, v80
	v_max_f32_e32 v164, v165, v164
	v_max3_f32 v164, v164, v82, v83
	v_max3_f32 v164, v164, v84, v85
	v_mfma_f32_32x32x16_bf16 v[48:63], v[138:141], v[234:237], v[48:63]
	ds_read_b64_tr_b16 v[234:235], v163 offset:0x1200
	ds_read_b64_tr_b16 v[236:237], v163 offset:0x1a00
	v_max3_f32 v164, v164, v86, v87
	v_max3_f32 v164, v164, v88, v89
	v_max3_f32 v164, v164, v90, v91
	v_max3_f32 v164, v164, v92, v93
	v_max3_f32 v164, v164, v94, v95
	v_mfma_f32_32x32x16_bf16 v[48:63], v[142:145], v[238:241], v[48:63]
	ds_read_b64_tr_b16 v[238:239], v163 offset:0x2200
	ds_read_b64_tr_b16 v[240:241], v163 offset:0x2a00
	ds_read_b64_tr_b16 v[246:247], v163 offset:0x3200
	ds_read_b64_tr_b16 v[248:249], v163 offset:0x3a00
	v_max3_f32 v164, v164, v64, v65
	v_max3_f32 v164, v164, v66, v67
	v_max3_f32 v164, v164, v68, v69
	v_max3_f32 v164, v164, v70, v71
	v_max3_f32 v164, v164, v72, v73
	s_waitcnt lgkmcnt(0)
	v_mfma_f32_32x32x16_bf16 v[48:63], v[146:149], v[242:245], v[48:63]
	v_max3_f32 v164, v164, v74, v75
	v_max3_f32 v164, v164, v76, v77
	v_max3_f32 v164, v164, v78, v79
	v_mfma_f32_32x32x16_bf16 v[32:47], v[134:137], v[230:233], v[32:47]
	ds_read_b64_tr_b16 v[230:231], v163 offset:0x400
	ds_read_b64_tr_b16 v[232:233], v163 offset:0xc00
	v_mov_b32_e32 v165, v164
	s_nop 1
	v_permlane32_swap_b32_e32 v164, v165
	v_max_f32_e32 v165, v165, v165
	v_max_f32_e32 v164, v164, v164
	v_max_f32_e32 v164, v164, v165
	v_mfma_f32_32x32x16_bf16 v[32:47], v[138:141], v[234:237], v[32:47]
	ds_read_b64_tr_b16 v[234:235], v163 offset:0x1400
	ds_read_b64_tr_b16 v[236:237], v163 offset:0x1c00
	v_max_f32_e32 v166, v195, v195
	v_sub_f32_e32 v165, v164, v195
	v_max_f32_e32 v164, v166, v164
	v_sub_f32_e32 v166, v195, v164
	v_mul_f32_e32 v166, 0x3dd53b94, v166
	v_mfma_f32_32x32x16_bf16 v[32:47], v[142:145], v[238:241], v[32:47]
	ds_read_b64_tr_b16 v[238:239], v163 offset:0x2400
	ds_read_b64_tr_b16 v[240:241], v163 offset:0x2c00
	ds_read_b64_tr_b16 v[242:243], v163 offset:0x3400
	ds_read_b64_tr_b16 v[244:245], v163 offset:0x3c00
	v_exp_f32_e32 v166, v166
	v_cmp_ge_f32_e32 vcc, s69, v165
	s_cmp_eq_u64 vcc, exec
	s_cselect_b64 s[8:9], -1, 0
	v_cndmask_b32_e64 v208, v166, 1.0, s[8:9]
	v_cndmask_b32_e64 v167, v164, v195, s[8:9]
	v_mul_f32_e32 v207, 0xbdd53b94, v167
	s_waitcnt lgkmcnt(0)
	v_mfma_f32_32x32x16_bf16 v[32:47], v[146:149], v[246:249], v[32:47]
	v_fmamk_f32 v80, v80, 0x3dd53b94, v207
	v_fmamk_f32 v81, v81, 0x3dd53b94, v207
	v_fmamk_f32 v82, v82, 0x3dd53b94, v207
	v_fmamk_f32 v83, v83, 0x3dd53b94, v207
	v_fmamk_f32 v84, v84, 0x3dd53b94, v207
	v_fmamk_f32 v85, v85, 0x3dd53b94, v207
	v_mfma_f32_32x32x16_bf16 v[16:31], v[134:137], v[230:233], v[16:31]
	ds_read_b64_tr_b16 v[230:231], v163 offset:0x600
	ds_read_b64_tr_b16 v[232:233], v163 offset:0xe00
	v_fmamk_f32 v86, v86, 0x3dd53b94, v207
	v_fmamk_f32 v87, v87, 0x3dd53b94, v207
	v_fmamk_f32 v88, v88, 0x3dd53b94, v207
	v_fmamk_f32 v89, v89, 0x3dd53b94, v207
	v_fmamk_f32 v90, v90, 0x3dd53b94, v207
	v_fmamk_f32 v91, v91, 0x3dd53b94, v207
	v_mfma_f32_32x32x16_bf16 v[16:31], v[138:141], v[234:237], v[16:31]
	ds_read_b64_tr_b16 v[234:235], v163 offset:0x1600
	ds_read_b64_tr_b16 v[236:237], v163 offset:0x1e00
	v_fmamk_f32 v92, v92, 0x3dd53b94, v207
	v_fmamk_f32 v93, v93, 0x3dd53b94, v207
	v_fmamk_f32 v94, v94, 0x3dd53b94, v207
	v_fmamk_f32 v95, v95, 0x3dd53b94, v207
	v_fmamk_f32 v217, v64, 0x3dd53b94, v207
	v_fmamk_f32 v218, v65, 0x3dd53b94, v207
	v_mfma_f32_32x32x16_bf16 v[16:31], v[142:145], v[238:241], v[16:31]
	ds_read_b64_tr_b16 v[238:239], v163 offset:0x2600
	ds_read_b64_tr_b16 v[240:241], v163 offset:0x2e00
	ds_read_b64_tr_b16 v[246:247], v163 offset:0x3600
	ds_read_b64_tr_b16 v[248:249], v163 offset:0x3e00
	v_fmamk_f32 v219, v66, 0x3dd53b94, v207
	v_fmamk_f32 v220, v67, 0x3dd53b94, v207
	v_fmamk_f32 v221, v68, 0x3dd53b94, v207
	v_fmamk_f32 v210, v69, 0x3dd53b94, v207
	v_fmamk_f32 v211, v70, 0x3dd53b94, v207
	v_fmamk_f32 v212, v71, 0x3dd53b94, v207
	s_waitcnt lgkmcnt(0)
	v_mfma_f32_32x32x16_bf16 v[16:31], v[146:149], v[242:245], v[16:31]
	v_fmamk_f32 v213, v72, 0x3dd53b94, v207
	v_fmamk_f32 v214, v73, 0x3dd53b94, v207
	v_fmamk_f32 v215, v74, 0x3dd53b94, v207
	v_fmamk_f32 v216, v75, 0x3dd53b94, v207
	v_exp_f32_e32 v195, v85
	v_mfma_f32_32x32x16_bf16 v[0:15], v[134:137], v[230:233], v[0:15]
	v_mov_b32_e32 v134, v167
	v_fmamk_f32 v209, v76, 0x3dd53b94, v207
	v_fmamk_f32 v222, v77, 0x3dd53b94, v207
	v_fmamk_f32 v223, v78, 0x3dd53b94, v207
	v_fmac_f32_e32 v207, 0x3dd53b94, v79
	v_exp_f32_e32 v135, v88
	v_mfma_f32_32x32x16_bf16 v[0:15], v[138:141], v[234:237], v[0:15]
	v_exp_f32_e32 v136, v92
	v_exp_f32_e32 v137, v89
	v_exp_f32_e32 v138, v90
	v_exp_f32_e32 v139, v93
	v_mfma_f32_32x32x16_bf16 v[0:15], v[142:145], v[238:241], v[0:15]
	v_exp_f32_e32 v140, v94
	v_exp_f32_e32 v141, v91
	v_exp_f32_e32 v142, v95
	v_exp_f32_e32 v143, v80
	v_exp_f32_e32 v144, v81
	v_mfma_f32_32x32x16_bf16 v[0:15], v[146:149], v[246:249], v[0:15]
	v_exp_f32_e32 v145, v82
	v_exp_f32_e32 v146, v86
	v_exp_f32_e32 v147, v83
	v_exp_f32_e32 v148, v84
	v_exp_f32_e32 v149, v87
	v_cmp_gt_f32_e32 vcc, 1.0, v208
	s_cbranch_vccz .LBB0_357
; __device__ __forceinline__ void qkt(f32x16& p0, f32x16& p1, const char* Ks, const char* Krs, const bf16x8* qr, const char* Qrs, int r32, int hi) {
;   p0 = f32x16{}; p1 = f32x16{};
; #pragma unroll
;   for (int d0 = 0; d0 < 8; ++d0) { const int cb = (d0 * 16 + hi * 8) * 2;
;     const bf16x8 b0 = *reinterpret_cast<const bf16x8*>(Ks + KSWZ(r32, cb));
;     const bf16x8 b1 = *reinterpret_cast<const bf16x8*>(Ks + KSWZ(32 + r32, cb));
;     p0 = __builtin_amdgcn_mfma_f32_32x32x16_bf16(b0, qr[d0], p0, 0, 0, 0);
;     p1 = __builtin_amdgcn_mfma_f32_32x32x16_bf16(b1, qr[d0], p1, 0, 0, 0); }
; #pragma unroll
;   for (int d0 = 0; d0 < 4; ++d0) { const int slot = d0 * 2 + hi;
;     const bf16x8 b0 = *reinterpret_cast<const bf16x8*>(Krs + RSWZ(r32, slot));
;     const bf16x8 b1 = *reinterpret_cast<const bf16x8*>(Krs + RSWZ(32 + r32, slot));
;     const bf16x8 qf = *reinterpret_cast<const bf16x8*>(Qrs + RSWZ(r32, slot));
;     p0 = __builtin_amdgcn_mfma_f32_32x32x16_bf16(b0, qf, p0, 0, 0, 0);
;     p1 = __builtin_amdgcn_mfma_f32_32x32x16_bf16(b1, qf, p1, 0, 0, 0); }
; }
	s_and_saveexec_b64 s[10:11], s[6:7]
	ds_write_b32 v160, v208 offset:128
	s_or_b64 exec, exec, s[10:11]
	s_waitcnt lgkmcnt(0)
	v_add_u32_e32 v246, v253, v128
	ds_read_b128 v[230:233], v246 offset:224
	ds_read_b128 v[234:237], v246 offset:192
	ds_read_b128 v[238:241], v246 offset:160
	ds_read_b128 v[242:245], v246 offset:128
	s_waitcnt lgkmcnt(3)
	v_pk_mul_f32 v[60:61], v[60:61], v[230:231]
	s_waitcnt lgkmcnt(2)
	v_pk_mul_f32 v[56:57], v[56:57], v[234:235]
	s_waitcnt lgkmcnt(1)
	v_pk_mul_f32 v[52:53], v[52:53], v[238:239]
	v_pk_mul_f32 v[62:63], v[62:63], v[232:233]
	v_pk_mul_f32 v[58:59], v[58:59], v[236:237]
	v_pk_mul_f32 v[54:55], v[54:55], v[240:241]
	s_waitcnt lgkmcnt(0)
	v_pk_mul_f32 v[50:51], v[50:51], v[244:245]
	v_pk_mul_f32 v[48:49], v[48:49], v[242:243]
	v_pk_mul_f32 v[44:45], v[44:45], v[230:231]
	v_pk_mul_f32 v[40:41], v[40:41], v[234:235]
	v_pk_mul_f32 v[36:37], v[36:37], v[238:239]
	v_pk_mul_f32 v[46:47], v[46:47], v[232:233]
	v_pk_mul_f32 v[42:43], v[42:43], v[236:237]
	v_pk_mul_f32 v[38:39], v[38:39], v[240:241]
	v_pk_mul_f32 v[34:35], v[34:35], v[244:245]
	v_pk_mul_f32 v[32:33], v[32:33], v[242:243]
	v_pk_mul_f32 v[28:29], v[28:29], v[230:231]
	v_pk_mul_f32 v[24:25], v[24:25], v[234:235]
	v_pk_mul_f32 v[20:21], v[20:21], v[238:239]
	v_pk_mul_f32 v[30:31], v[30:31], v[232:233]
	v_pk_mul_f32 v[26:27], v[26:27], v[236:237]
	v_pk_mul_f32 v[22:23], v[22:23], v[240:241]
	v_pk_mul_f32 v[18:19], v[18:19], v[244:245]
	v_pk_mul_f32 v[16:17], v[16:17], v[242:243]
	v_pk_mul_f32 v[12:13], v[12:13], v[230:231]
	v_pk_mul_f32 v[8:9], v[8:9], v[234:235]
	v_pk_mul_f32 v[4:5], v[4:5], v[238:239]
	v_pk_mul_f32 v[14:15], v[14:15], v[232:233]
	v_pk_mul_f32 v[10:11], v[10:11], v[236:237]
	v_pk_mul_f32 v[6:7], v[6:7], v[240:241]
	v_pk_mul_f32 v[2:3], v[2:3], v[244:245]
	v_pk_mul_f32 v[0:1], v[0:1], v[242:243]
.LBB0_357:
	s_waitcnt vmcnt(0)
	s_waitcnt lgkmcnt(0)
	s_barrier
	s_add_u32 s46, s70, 0x20000
	s_addc_u32 s47, s71, 0
	ds_read_b128 v[64:67], v169 offset:32768
	ds_read_b128 v[68:71], v169 offset:40960
	ds_read_b128 v[224:227], v170 offset:32768
	ds_read_b128 v[228:231], v170 offset:40960
	ds_read_b128 v[240:243], v171 offset:32768
	ds_read_b128 v[244:247], v171 offset:40960
	v_exp_f32_e32 v159, v210
	v_add_f32_e32 v210, 0, v143
	s_add_u32 m0, s98, 0xc000
	s_waitcnt lgkmcnt(5)
	v_mfma_f32_32x32x16_bf16 v[80:95], v[64:67], v[124:127], 0
	global_load_lds_dwordx4 v130, s[70:71]
	v_add_f32_e32 v210, v144, v210
	v_add_f32_e32 v210, v145, v210
	v_add_f32_e32 v210, v147, v210
	v_add_f32_e32 v210, v148, v210
	v_add_f32_e32 v210, v195, v210
	v_add_f32_e32 v210, v146, v210
	v_add_f32_e32 v210, v149, v210
	s_add_u32 m0, s98, 0xe000
	s_waitcnt lgkmcnt(4)
	v_mfma_f32_32x32x16_bf16 v[64:79], v[68:71], v[124:127], 0
	global_load_lds_dwordx4 v130, s[46:47]
	v_add_f32_e32 v210, v135, v210
	v_add_f32_e32 v210, v137, v210
	v_add_f32_e32 v210, v138, v210
	v_add_f32_e32 v210, v141, v210
	v_exp_f32_e32 v150, v217
	v_add_f32_e32 v210, v136, v210
	v_exp_f32_e32 v151, v218
	s_add_u32 m0, s98, 0x12000
	s_waitcnt lgkmcnt(3)
	v_mfma_f32_32x32x16_bf16 v[80:95], v[224:227], v[120:123], v[80:95]
	global_load_lds_dwordx4 v132, s[72:73]
	v_add_f32_e32 v210, v139, v210
	v_exp_f32_e32 v156, v219
	v_add_f32_e32 v210, v140, v210
	v_exp_f32_e32 v157, v220
	v_add_f32_e32 v210, v142, v210
	v_exp_f32_e32 v158, v221
	v_add_f32_e32 v210, v150, v210
	s_mov_b32 m0, s98
	s_waitcnt lgkmcnt(2)
	v_mfma_f32_32x32x16_bf16 v[64:79], v[228:231], v[120:123], v[64:79]
	global_load_lds_dwordx4 v131, s[70:71]
	ds_read_b128 v[224:227], v172 offset:32768
	ds_read_b128 v[228:231], v172 offset:40960
	v_add_f32_e32 v210, v151, v210
	v_exp_f32_e32 v217, v211
	v_add_f32_e32 v210, v156, v210
	v_exp_f32_e32 v218, v212
	v_add_f32_e32 v210, v157, v210
	v_exp_f32_e32 v219, v213
	s_add_u32 m0, s98, 0x2000
	s_waitcnt lgkmcnt(3)
	v_mfma_f32_32x32x16_bf16 v[80:95], v[240:243], v[116:119], v[80:95]
	global_load_lds_dwordx4 v131, s[46:47]
	s_add_u32 s70, s70, 0x40000
	s_addc_u32 s71, s71, 0
	s_add_u32 s72, s72, 0x2000
	s_addc_u32 s73, s73, 0
	v_add_f32_e32 v210, v158, v210
	v_exp_f32_e32 v214, v214
	v_add_f32_e32 v210, v159, v210
	v_exp_f32_e32 v215, v215
	v_add_f32_e32 v210, v217, v210
	v_exp_f32_e32 v216, v216
	v_add_f32_e32 v210, v218, v210
	s_waitcnt lgkmcnt(2)
	v_mfma_f32_32x32x16_bf16 v[64:79], v[244:247], v[116:119], v[64:79]
	ds_read_b128 v[240:243], v173 offset:32768
	ds_read_b128 v[244:247], v173 offset:40960
	v_exp_f32_e32 v209, v209
	v_add_f32_e32 v210, v219, v210
	v_exp_f32_e32 v220, v222
	v_add_f32_e32 v210, v214, v210
	v_exp_f32_e32 v221, v223
	v_add_f32_e32 v210, v215, v210
	s_waitcnt lgkmcnt(3)
	v_mfma_f32_32x32x16_bf16 v[80:95], v[224:227], v[112:115], v[80:95]
	v_exp_f32_e32 v207, v207
	v_add_f32_e32 v210, v216, v210
	v_add_f32_e32 v210, v209, v210
	v_add_f32_e32 v210, v220, v210
	v_add_f32_e32 v210, v221, v210
	v_cvt_pk_bf16_f32 v211, v145, v147
	v_cvt_pk_bf16_f32 v212, v148, v195
	s_waitcnt lgkmcnt(2)
	v_mfma_f32_32x32x16_bf16 v[64:79], v[228:231], v[112:115], v[64:79]
	ds_read_b128 v[224:227], v174 offset:32768
	ds_read_b128 v[228:231], v174 offset:40960
	v_cvt_pk_bf16_f32 v213, v146, v149
	v_cvt_pk_bf16_f32 v145, v138, v141
	v_cvt_pk_bf16_f32 v146, v136, v139
	v_cvt_pk_bf16_f32 v147, v140, v142
	v_cvt_pk_bf16_f32 v136, v150, v151
	v_cvt_pk_bf16_f32 v138, v158, v159
	s_waitcnt lgkmcnt(3)
	v_mfma_f32_32x32x16_bf16 v[80:95], v[240:243], v[108:111], v[80:95]
	v_cvt_pk_bf16_f32 v139, v217, v218
	v_cvt_pk_bf16_f32 v140, v219, v214
	v_cvt_pk_bf16_f32 v141, v215, v216
	v_cvt_pk_bf16_f32 v142, v209, v220
	v_permlane32_swap_b32_e32 v211, v213
	v_permlane32_swap_b32_e32 v145, v147
	s_waitcnt lgkmcnt(2)
; __device__ __forceinline__ void qkt(f32x16& p0, f32x16& p1, const char* Ks, const char* Krs, const bf16x8* qr, const char* Qrs, int r32, int hi) {
;   p0 = f32x16{}; p1 = f32x16{};
; #pragma unroll
;   for (int d0 = 0; d0 < 8; ++d0) { const int cb = (d0 * 16 + hi * 8) * 2;
;     const bf16x8 b0 = *reinterpret_cast<const bf16x8*>(Ks + KSWZ(r32, cb));
;     const bf16x8 b1 = *reinterpret_cast<const bf16x8*>(Ks + KSWZ(32 + r32, cb));
;     p0 = __builtin_amdgcn_mfma_f32_32x32x16_bf16(b0, qr[d0], p0, 0, 0, 0);
;     p1 = __builtin_amdgcn_mfma_f32_32x32x16_bf16(b1, qr[d0], p1, 0, 0, 0); }
; #pragma unroll
;   for (int d0 = 0; d0 < 4; ++d0) { const int slot = d0 * 2 + hi;
;     const bf16x8 b0 = *reinterpret_cast<const bf16x8*>(Krs + RSWZ(r32, slot));
;     const bf16x8 b1 = *reinterpret_cast<const bf16x8*>(Krs + RSWZ(32 + r32, slot));
;     const bf16x8 qf = *reinterpret_cast<const bf16x8*>(Qrs + RSWZ(r32, slot));
;     p0 = __builtin_amdgcn_mfma_f32_32x32x16_bf16(b0, qf, p0, 0, 0, 0);
;     p1 = __builtin_amdgcn_mfma_f32_32x32x16_bf16(b1, qf, p1, 0, 0, 0); }
; }
; __device__ __forceinline__ int v_st(int k, int c) { const int kk = (k & ~0xC) | ((k & 4) << 1) | ((k & 8) >> 1); return ((kk >> 3) * 4 + (c >> 5)) * 512 + ((kk & 7) * 32 + (c & 31)) * 2; }
; __device__ __forceinline__ int v_rd_base(int lane) { return ((lane & 3) << 3) | (((lane >> 2) & 3) << 6) | (((lane >> 4) & 1) << 5) | (((lane >> 5) & 1) << 8); }
; template <int OFF> __device__ __forceinline__ s16x4 tr_read(int vb) {
;   s16x4 r; asm volatile("ds_read_b64_tr_b16 %0, %1 offset:%2" : "=&v"(r) : "v"(vb), "i"(OFF) : "memory"); return r;
; }
; template <int D0> __device__ __forceinline__ void pv_one(f32x16& od, int vb, bf16x8 pa0, bf16x8 pa1, bf16x8 pa2, bf16x8 pa3) {
;   const s16x4 l0 = tr_read<v_rd_off(D0, 0, 0)>(vb), h0 = tr_read<v_rd_off(D0, 0, 1)>(vb), l1 = tr_read<v_rd_off(D0, 1, 0)>(vb), h1 = tr_read<v_rd_off(D0, 1, 1)>(vb);
;   const s16x4 l2 = tr_read<v_rd_off(D0, 2, 0)>(vb), h2 = tr_read<v_rd_off(D0, 2, 1)>(vb), l3 = tr_read<v_rd_off(D0, 3, 0)>(vb), h3 = tr_read<v_rd_off(D0, 3, 1)>(vb);
;   asm volatile("s_waitcnt lgkmcnt(0)" ::: "memory"); SBAR();
;     ...
;   od = __builtin_amdgcn_mfma_f32_32x32x16_bf16(pa0, PK(l0, h0), od, 0, 0, 0);
;   od = __builtin_amdgcn_mfma_f32_32x32x16_bf16(pa1, PK(l1, h1), od, 0, 0, 0);
;   od = __builtin_amdgcn_mfma_f32_32x32x16_bf16(pa2, PK(l2, h2), od, 0, 0, 0);
	v_mfma_f32_32x32x16_bf16 v[64:79], v[244:247], v[108:111], v[64:79]
	ds_read_b128 v[240:243], v175 offset:32768
	ds_read_b128 v[244:247], v175 offset:40960
	v_permlane32_swap_b32_e32 v136, v138
	v_permlane32_swap_b32_e32 v140, v142
	s_waitcnt lgkmcnt(3)
	v_mfma_f32_32x32x16_bf16 v[80:95], v[224:227], v[104:107], v[80:95]
	s_waitcnt lgkmcnt(2)
	v_mfma_f32_32x32x16_bf16 v[64:79], v[228:231], v[104:107], v[64:79]
	ds_read_b128 v[224:227], v176 offset:32768
	ds_read_b128 v[228:231], v176 offset:40960
	s_waitcnt lgkmcnt(3)
	v_mfma_f32_32x32x16_bf16 v[80:95], v[240:243], v[100:103], v[80:95]
	s_waitcnt lgkmcnt(2)
	v_mfma_f32_32x32x16_bf16 v[64:79], v[244:247], v[100:103], v[64:79]
	ds_read_b128 v[240:243], v177
	ds_read_b128 v[244:247], v178
	ds_read_b128 v[248:251], v192
	s_waitcnt lgkmcnt(4)
	v_mfma_f32_32x32x16_bf16 v[80:95], v[224:227], v[96:99], v[80:95]
	s_waitcnt lgkmcnt(3)
	v_mfma_f32_32x32x16_bf16 v[64:79], v[228:231], v[96:99], v[64:79]
	ds_read_b128 v[224:227], v179
	ds_read_b128 v[228:231], v180
	ds_read_b128 v[232:235], v191
	s_waitcnt lgkmcnt(3)
	v_mfma_f32_32x32x16_bf16 v[80:95], v[240:243], v[248:251], v[80:95]
	s_waitcnt lgkmcnt(3)
	v_mfma_f32_32x32x16_bf16 v[64:79], v[244:247], v[248:251], v[64:79]
	ds_read_b128 v[240:243], v182
	ds_read_b128 v[244:247], v183
	ds_read_b128 v[248:251], v168
	s_waitcnt lgkmcnt(3)
	v_mfma_f32_32x32x16_bf16 v[80:95], v[224:227], v[232:235], v[80:95]
	s_waitcnt lgkmcnt(3)
	v_mfma_f32_32x32x16_bf16 v[64:79], v[228:231], v[232:235], v[64:79]
	ds_read_b128 v[224:227], v185
	ds_read_b128 v[228:231], v186
	ds_read_b128 v[232:235], v187
	s_waitcnt lgkmcnt(3)
	v_mfma_f32_32x32x16_bf16 v[80:95], v[240:243], v[248:251], v[80:95]
	s_waitcnt lgkmcnt(3)
	v_mfma_f32_32x32x16_bf16 v[64:79], v[244:247], v[248:251], v[64:79]
	s_waitcnt lgkmcnt(0)
	v_mfma_f32_32x32x16_bf16 v[80:95], v[224:227], v[232:235], v[80:95]
	v_add_f32_e32 v225, v207, v210
	v_mov_b32_e32 v226, v225
	s_nop 1
	v_permlane32_swap_b32_e32 v225, v226
	v_cvt_pk_bf16_f32 v210, v143, v144
	v_cvt_pk_bf16_f32 v144, v135, v137
	v_cvt_pk_bf16_f32 v137, v156, v157
	s_waitcnt lgkmcnt(0)
	v_mfma_f32_32x32x16_bf16 v[64:79], v[228:231], v[232:235], v[64:79]
	v_cvt_pk_bf16_f32 v143, v221, v207
	v_permlane32_swap_b32_e32 v210, v212
	v_permlane32_swap_b32_e32 v144, v146
	v_permlane32_swap_b32_e32 v137, v139
	v_permlane32_swap_b32_e32 v141, v143
	ds_read_b64_tr_b16 v[240:241], v162 offset:0
	ds_read_b64_tr_b16 v[242:243], v162 offset:0x800
	ds_read_b64_tr_b16 v[244:245], v162 offset:0x1000
	ds_read_b64_tr_b16 v[246:247], v162 offset:0x1800
	ds_read_b64_tr_b16 v[248:249], v162 offset:0x2000
	ds_read_b64_tr_b16 v[250:251], v162 offset:0x2800
	ds_read_b64_tr_b16 v[148:149], v162 offset:0x3000
	ds_read_b64_tr_b16 v[150:151], v162 offset:0x3800
	s_waitcnt lgkmcnt(0)
	s_nop 0
	v_mfma_f32_32x32x16_bf16 v[48:63], v[210:213], v[240:243], v[48:63]
	ds_read_b64_tr_b16 v[240:241], v162 offset:0x200
	ds_read_b64_tr_b16 v[242:243], v162 offset:0xa00
	v_max_f32_e32 v164, v81, v81
	v_max_f32_e32 v165, v80, v80
	v_max_f32_e32 v164, v165, v164
	v_max3_f32 v164, v164, v82, v83
	v_max3_f32 v164, v164, v84, v85
	v_mfma_f32_32x32x16_bf16 v[48:63], v[144:147], v[244:247], v[48:63]
	ds_read_b64_tr_b16 v[244:245], v162 offset:0x1200
	ds_read_b64_tr_b16 v[246:247], v162 offset:0x1a00
	v_max3_f32 v164, v164, v86, v87
	v_max3_f32 v164, v164, v88, v89
	v_max3_f32 v164, v164, v90, v91
	v_max3_f32 v164, v164, v92, v93
	v_max3_f32 v164, v164, v94, v95
	v_mfma_f32_32x32x16_bf16 v[48:63], v[136:139], v[248:251], v[48:63]
	ds_read_b64_tr_b16 v[248:249], v162 offset:0x2200
	ds_read_b64_tr_b16 v[250:251], v162 offset:0x2a00
	ds_read_b64_tr_b16 v[156:157], v162 offset:0x3200
	ds_read_b64_tr_b16 v[158:159], v162 offset:0x3a00
	v_max3_f32 v164, v164, v64, v65
	v_max3_f32 v164, v164, v66, v67
	v_max3_f32 v164, v164, v68, v69
	v_max3_f32 v164, v164, v70, v71
	v_max3_f32 v164, v164, v72, v73
	s_waitcnt lgkmcnt(0)
	v_mfma_f32_32x32x16_bf16 v[48:63], v[140:143], v[148:151], v[48:63]
	v_max3_f32 v164, v164, v74, v75
	v_max3_f32 v164, v164, v76, v77
	v_max3_f32 v164, v164, v78, v79
	v_mfma_f32_32x32x16_bf16 v[32:47], v[210:213], v[240:243], v[32:47]
	ds_read_b64_tr_b16 v[148:149], v162 offset:0x400
	ds_read_b64_tr_b16 v[150:151], v162 offset:0xc00
	ds_read_b64_tr_b16 v[240:241], v162 offset:0x1400
	ds_read_b64_tr_b16 v[242:243], v162 offset:0x1c00
	v_mov_b32_e32 v165, v164
	s_nop 1
	v_permlane32_swap_b32_e32 v164, v165
	v_max_f32_e32 v165, v165, v165
	v_max_f32_e32 v164, v164, v164
	v_max_f32_e32 v164, v164, v165
	v_mfma_f32_32x32x16_bf16 v[32:47], v[144:147], v[244:247], v[32:47]
	ds_read_b64_tr_b16 v[244:245], v162 offset:0x2400
	ds_read_b64_tr_b16 v[246:247], v162 offset:0x2c00
	v_max_f32_e32 v166, v134, v134
	v_sub_f32_e32 v165, v164, v134
	v_max_f32_e32 v164, v166, v164
	v_sub_f32_e32 v166, v134, v164
	v_mul_f32_e32 v166, 0x3dd53b94, v166
	v_mfma_f32_32x32x16_bf16 v[32:47], v[136:139], v[248:251], v[32:47]
	ds_read_b64_tr_b16 v[248:249], v162 offset:0x3400
	ds_read_b64_tr_b16 v[250:251], v162 offset:0x3c00
	v_exp_f32_e32 v166, v166
	v_cmp_ge_f32_e32 vcc, s69, v165
	s_cmp_eq_u64 vcc, exec
	s_cselect_b64 s[8:9], -1, 0
	v_cndmask_b32_e64 v207, v166, 1.0, s[8:9]
	v_cndmask_b32_e64 v195, v164, v134, s[8:9]
	v_mul_f32_e32 v168, 0xbdd53b94, v195
	v_mov_b32_e32 v187, v168
	s_waitcnt lgkmcnt(0)
; __device__ __forceinline__ void partialSM(f32x16& p0, f32x16& p1, float& m_reg, float& mn, float& alpha) {
;   constexpr float C = ATT_SCALE * 1.4426950408889634f;
;   float pmax = p0[0];
; #pragma unroll
;   for (int r = 1; r < 16; ++r) pmax = fmaxf(pmax, p0[r]);
; #pragma unroll
;   for (int r = 0; r < 16; ++r) pmax = fmaxf(pmax, p1[r]);
;   { auto rr = __builtin_amdgcn_permlane32_swap(__float_as_uint(pmax), __float_as_uint(pmax), false, false);
;     pmax = fmaxf(__uint_as_float(rr[0]), __uint_as_float(rr[1])); }
;   if (__builtin_expect(__all(pmax - m_reg <= ATT_THR / ATT_SCALE), 1)) { mn = m_reg; alpha = 1.f; }
;   else { mn = fmaxf(m_reg, pmax); alpha = __builtin_amdgcn_exp2f((m_reg - mn) * C); m_reg = mn; }
;   const float mnC = -mn * C;
; #pragma unroll
;   for (int r = 0; r < 16; ++r) p0[r] = fmaf(p0[r], C, mnC);
; #pragma unroll
;   for (int r = 0; r < 16; ++r) p1[r] = fmaf(p1[r], C, mnC);
; #pragma unroll
;   for (int r = 0; r < 16; ++r) p0[r] = __builtin_amdgcn_exp2f(p0[r]);
	v_mfma_f32_32x32x16_bf16 v[32:47], v[140:143], v[156:159], v[32:47]
	v_fmamk_f32 v80, v80, 0x3dd53b94, v168
	v_fmamk_f32 v81, v81, 0x3dd53b94, v168
	v_fmamk_f32 v82, v82, 0x3dd53b94, v168
	v_fmamk_f32 v83, v83, 0x3dd53b94, v168
	v_fmamk_f32 v84, v84, 0x3dd53b94, v168
	v_fmamk_f32 v85, v85, 0x3dd53b94, v168
	v_mfma_f32_32x32x16_bf16 v[16:31], v[210:213], v[148:151], v[16:31]
	ds_read_b64_tr_b16 v[148:149], v162 offset:0x600
	ds_read_b64_tr_b16 v[150:151], v162 offset:0xe00
	ds_read_b64_tr_b16 v[156:157], v162 offset:0x1600
	ds_read_b64_tr_b16 v[158:159], v162 offset:0x1e00
	v_fmamk_f32 v86, v86, 0x3dd53b94, v168
	v_fmamk_f32 v87, v87, 0x3dd53b94, v168
	v_fmamk_f32 v88, v88, 0x3dd53b94, v168
	v_fmamk_f32 v89, v89, 0x3dd53b94, v168
	v_fmamk_f32 v90, v90, 0x3dd53b94, v168
	v_fmamk_f32 v91, v91, 0x3dd53b94, v168
	v_mfma_f32_32x32x16_bf16 v[16:31], v[144:147], v[240:243], v[16:31]
	ds_read_b64_tr_b16 v[240:241], v162 offset:0x2600
	ds_read_b64_tr_b16 v[242:243], v162 offset:0x2e00
	v_fmamk_f32 v92, v92, 0x3dd53b94, v168
	v_fmamk_f32 v93, v93, 0x3dd53b94, v168
	v_fmamk_f32 v94, v94, 0x3dd53b94, v168
	v_fmac_f32_e32 v187, 0x3dd53b94, v95
	v_fmamk_f32 v134, v72, 0x3dd53b94, v168
	v_fmamk_f32 v135, v73, 0x3dd53b94, v168
	v_mfma_f32_32x32x16_bf16 v[16:31], v[136:139], v[244:247], v[16:31]
	ds_read_b64_tr_b16 v[244:245], v162 offset:0x3600
	ds_read_b64_tr_b16 v[246:247], v162 offset:0x3e00
	v_exp_f32_e32 v217, v81
	v_exp_f32_e32 v218, v82
	v_exp_f32_e32 v220, v83
	v_exp_f32_e32 v221, v84
	s_waitcnt lgkmcnt(0)
	v_mfma_f32_32x32x16_bf16 v[16:31], v[140:143], v[248:251], v[16:31]
	v_exp_f32_e32 v223, v85
	v_exp_f32_e32 v222, v86
	v_exp_f32_e32 v224, v87
	v_exp_f32_e32 v209, v88
	v_mfma_f32_32x32x16_bf16 v[0:15], v[210:213], v[148:151], v[0:15]
	v_fmamk_f32 v148, v74, 0x3dd53b94, v168
	v_fmamk_f32 v149, v75, 0x3dd53b94, v168
	v_exp_f32_e32 v214, v91
	v_exp_f32_e32 v215, v93
	v_exp_f32_e32 v216, v94
	v_mfma_f32_32x32x16_bf16 v[0:15], v[144:147], v[156:159], v[0:15]
	v_fmamk_f32 v146, v64, 0x3dd53b94, v168
	v_fmamk_f32 v147, v65, 0x3dd53b94, v168
	v_fmamk_f32 v144, v66, 0x3dd53b94, v168
	v_fmamk_f32 v145, v67, 0x3dd53b94, v168
	v_exp_f32_e32 v219, v187
	v_exp_f32_e32 v213, v80
	v_mfma_f32_32x32x16_bf16 v[0:15], v[136:139], v[240:243], v[0:15]
	v_fmamk_f32 v136, v70, 0x3dd53b94, v168
	v_fmamk_f32 v137, v71, 0x3dd53b94, v168
	v_fmamk_f32 v138, v78, 0x3dd53b94, v168
	v_fmamk_f32 v139, v79, 0x3dd53b94, v168
	v_exp_f32_e32 v210, v89
	v_exp_f32_e32 v211, v90
	v_mfma_f32_32x32x16_bf16 v[0:15], v[140:143], v[244:247], v[0:15]
	v_fmamk_f32 v140, v68, 0x3dd53b94, v168
	v_fmamk_f32 v141, v69, 0x3dd53b94, v168
	v_fmamk_f32 v142, v76, 0x3dd53b94, v168
	v_fmamk_f32 v143, v77, 0x3dd53b94, v168
	v_exp_f32_e32 v212, v92
	v_cmp_gt_f32_e32 vcc, 1.0, v207
	s_cbranch_vccz .LBB0_361
	s_and_saveexec_b64 s[10:11], s[6:7]
	ds_write_b32 v160, v207 offset:128
	s_or_b64 exec, exec, s[10:11]
	s_waitcnt lgkmcnt(0)
	v_add_u32_e32 v150, v253, v128
	ds_read_b128 v[240:243], v150 offset:224
	ds_read_b128 v[244:247], v150 offset:192
	ds_read_b128 v[248:251], v150 offset:160
	ds_read_b128 v[156:159], v150 offset:128
	s_waitcnt lgkmcnt(3)
	v_pk_mul_f32 v[60:61], v[60:61], v[240:241]
	s_waitcnt lgkmcnt(2)
	v_pk_mul_f32 v[56:57], v[56:57], v[244:245]
	s_waitcnt lgkmcnt(1)
	v_pk_mul_f32 v[52:53], v[52:53], v[248:249]
	v_pk_mul_f32 v[62:63], v[62:63], v[242:243]
	v_pk_mul_f32 v[58:59], v[58:59], v[246:247]
	v_pk_mul_f32 v[54:55], v[54:55], v[250:251]
	s_waitcnt lgkmcnt(0)
	v_pk_mul_f32 v[50:51], v[50:51], v[158:159]
	v_pk_mul_f32 v[48:49], v[48:49], v[156:157]
	v_pk_mul_f32 v[44:45], v[44:45], v[240:241]
	v_pk_mul_f32 v[40:41], v[40:41], v[244:245]
	v_pk_mul_f32 v[36:37], v[36:37], v[248:249]
	v_pk_mul_f32 v[46:47], v[46:47], v[242:243]
	v_pk_mul_f32 v[42:43], v[42:43], v[246:247]
	v_pk_mul_f32 v[38:39], v[38:39], v[250:251]
	v_pk_mul_f32 v[34:35], v[34:35], v[158:159]
	v_pk_mul_f32 v[32:33], v[32:33], v[156:157]
	v_pk_mul_f32 v[28:29], v[28:29], v[240:241]
	v_pk_mul_f32 v[24:25], v[24:25], v[244:245]
	v_pk_mul_f32 v[20:21], v[20:21], v[248:249]
	v_pk_mul_f32 v[30:31], v[30:31], v[242:243]
	v_pk_mul_f32 v[26:27], v[26:27], v[246:247]
	v_pk_mul_f32 v[22:23], v[22:23], v[250:251]
	v_pk_mul_f32 v[18:19], v[18:19], v[158:159]
	v_pk_mul_f32 v[16:17], v[16:17], v[156:157]
	v_pk_mul_f32 v[12:13], v[12:13], v[240:241]
	v_pk_mul_f32 v[8:9], v[8:9], v[244:245]
	v_pk_mul_f32 v[4:5], v[4:5], v[248:249]
	v_pk_mul_f32 v[14:15], v[14:15], v[242:243]
	v_pk_mul_f32 v[10:11], v[10:11], v[246:247]
	v_pk_mul_f32 v[6:7], v[6:7], v[250:251]
	v_pk_mul_f32 v[2:3], v[2:3], v[158:159]
	v_pk_mul_f32 v[0:1], v[0:1], v[156:157]

; #define SBAR() __builtin_amdgcn_sched_barrier(0)
; __device__ __forceinline__ void qkt(f32x16& p0, f32x16& p1, const char* Ks, const char* Krs, const bf16x8* qr, const char* Qrs, int r32, int hi) {
;   p0 = f32x16{}; p1 = f32x16{};
; #pragma unroll
;   for (int d0 = 0; d0 < 8; ++d0) { const int cb = (d0 * 16 + hi * 8) * 2;
;     const bf16x8 b0 = *reinterpret_cast<const bf16x8*>(Ks + KSWZ(r32, cb));
;     const bf16x8 b1 = *reinterpret_cast<const bf16x8*>(Ks + KSWZ(32 + r32, cb));
;     p0 = __builtin_amdgcn_mfma_f32_32x32x16_bf16(b0, qr[d0], p0, 0, 0, 0);
;     p1 = __builtin_amdgcn_mfma_f32_32x32x16_bf16(b1, qr[d0], p1, 0, 0, 0); }
; #pragma unroll
;   for (int d0 = 0; d0 < 4; ++d0) { const int slot = d0 * 2 + hi;
;     const bf16x8 b0 = *reinterpret_cast<const bf16x8*>(Krs + RSWZ(r32, slot));
;     const bf16x8 b1 = *reinterpret_cast<const bf16x8*>(Krs + RSWZ(32 + r32, slot));
;     const bf16x8 qf = *reinterpret_cast<const bf16x8*>(Qrs + RSWZ(r32, slot));
;     p0 = __builtin_amdgcn_mfma_f32_32x32x16_bf16(b0, qf, p0, 0, 0, 0);
;     p1 = __builtin_amdgcn_mfma_f32_32x32x16_bf16(b1, qf, p1, 0, 0, 0); }
; }
; __device__ __forceinline__ void attn_item(const u16* __restrict__ Qb, const u16* __restrict__ Kh, const u16* __restrict__ Vh, const u16* __restrict__ Kr,
;                                           const u16* __restrict__ gaP, u16* mgP, int seq, char* lds) {
;     ...
;   SBAR(); qkt(pB0, pB1, K_lds + SHM_K, R_lds + SHM_KR, qr, Q_lds, r32, hi);
;   finishSM(pA0, pA1, alA, l_reg, pa0, pa1, pa2, pa3); SBAR();
;   pv_d0(o, vb0, pa0, pa1, pa2, pa3); partialSM(pB0, pB1, m_reg, mnB, alB);
.LBB0_363:
	v_or_b32_e32 v196, 0x12000, v181
	v_or_b32_e32 v197, 0x13000, v181
	v_add_u32_e32 v198, v155, v181
	v_or_b32_e32 v199, 0x12000, v184
	v_add_u32_e32 v204, v155, v184
	s_add_u32 s46, s70, 0x20000
	s_addc_u32 s47, s71, 0
	s_add_u32 m0, s98, 0x4000
	s_nop 0
	global_load_lds_dwordx4 v131, s[70:71]
	s_add_u32 m0, s98, 0x6000
	s_nop 0
	global_load_lds_dwordx4 v131, s[46:47]
	ds_read_b128 v[64:67], v169 offset:49152
	ds_read_b128 v[68:71], v169 offset:57344
	v_exp_f32_e32 v146, v146
	v_exp_f32_e32 v147, v147
	v_exp_f32_e32 v144, v144
	s_waitcnt lgkmcnt(1)
	v_mfma_f32_32x32x16_bf16 v[80:95], v[64:67], v[124:127], 0
	v_exp_f32_e32 v145, v145
	v_exp_f32_e32 v140, v140
	v_exp_f32_e32 v134, v134
	v_exp_f32_e32 v135, v135
	s_waitcnt lgkmcnt(0)
	v_mfma_f32_32x32x16_bf16 v[64:79], v[68:71], v[124:127], 0
	ds_read_b128 v[124:127], v170 offset:49152
	ds_read_b128 v[130:133], v170 offset:57344
	s_waitcnt lgkmcnt(1)
	v_mfma_f32_32x32x16_bf16 v[80:95], v[124:127], v[120:123], v[80:95]
	s_waitcnt lgkmcnt(0)
	v_mfma_f32_32x32x16_bf16 v[64:79], v[130:133], v[120:123], v[64:79]
	ds_read_b128 v[120:123], v171 offset:49152
	ds_read_b128 v[124:127], v171 offset:57344
	s_waitcnt lgkmcnt(1)
	v_mfma_f32_32x32x16_bf16 v[80:95], v[120:123], v[116:119], v[80:95]
	s_waitcnt lgkmcnt(0)
	v_mfma_f32_32x32x16_bf16 v[64:79], v[124:127], v[116:119], v[64:79]
	ds_read_b128 v[116:119], v172 offset:49152
	ds_read_b128 v[120:123], v172 offset:57344
	s_waitcnt lgkmcnt(1)
	v_mfma_f32_32x32x16_bf16 v[80:95], v[116:119], v[112:115], v[80:95]
	s_waitcnt lgkmcnt(0)
	v_mfma_f32_32x32x16_bf16 v[64:79], v[120:123], v[112:115], v[64:79]
	ds_read_b128 v[112:115], v173 offset:49152
	ds_read_b128 v[116:119], v173 offset:57344
	s_waitcnt lgkmcnt(1)
	v_mfma_f32_32x32x16_bf16 v[80:95], v[112:115], v[108:111], v[80:95]
	ds_read_b128 v[112:115], v174 offset:49152
	s_waitcnt lgkmcnt(1)
	v_mfma_f32_32x32x16_bf16 v[64:79], v[116:119], v[108:111], v[64:79]
	ds_read_b128 v[108:111], v174 offset:57344
	ds_read_b128 v[116:119], v175 offset:49152
	ds_read_b128 v[120:123], v175 offset:57344
	ds_read_b128 v[124:127], v176 offset:49152
	ds_read_b128 v[130:133], v176 offset:57344
	ds_read_b128 v[164:167], v193
	ds_read_b128 v[168:171], v194
	s_waitcnt lgkmcnt(7)
	v_mfma_f32_32x32x16_bf16 v[80:95], v[112:115], v[104:107], v[80:95]
	ds_read_b128 v[112:115], v192
	ds_read_b128 v[172:175], v189
	ds_read_b128 v[176:179], v190
	ds_read_b128 v[180:183], v191
	ds_read_b128 v[184:187], v196
	ds_read_b128 v[188:191], v197
	ds_read_b128 v[226:229], v198
	ds_read_b128 v[196:199], v199
	s_waitcnt lgkmcnt(14)
	v_mfma_f32_32x32x16_bf16 v[64:79], v[108:111], v[104:107], v[64:79]
	ds_read_b128 v[104:107], v203
	ds_read_b128 v[108:111], v204
	s_waitcnt lgkmcnt(14)
	v_mfma_f32_32x32x16_bf16 v[80:95], v[116:119], v[100:103], v[80:95]
	v_exp_f32_e32 v118, v141
	v_exp_f32_e32 v119, v136
	v_exp_f32_e32 v136, v137
	v_exp_f32_e32 v137, v148
	v_exp_f32_e32 v141, v149
	v_cvt_pk_bf16_f32 v116, v146, v147
	v_cvt_pk_bf16_f32 v117, v144, v145
	v_mfma_f32_32x32x16_bf16 v[64:79], v[120:123], v[100:103], v[64:79]
	v_add_f32_e32 v100, 0, v213
	v_add_f32_e32 v100, v217, v100
	v_add_f32_e32 v100, v218, v100
	v_add_f32_e32 v100, v220, v100
	v_add_f32_e32 v100, v221, v100
	v_add_f32_e32 v100, v223, v100
	v_add_f32_e32 v100, v222, v100
	s_waitcnt lgkmcnt(13)
	v_mfma_f32_32x32x16_bf16 v[80:95], v[124:127], v[96:99], v[80:95]
	v_add_f32_e32 v100, v224, v100
	v_add_f32_e32 v100, v209, v100
	v_add_f32_e32 v100, v210, v100
	v_exp_f32_e32 v102, v142
	v_exp_f32_e32 v103, v143
	v_exp_f32_e32 v123, v138
	v_exp_f32_e32 v138, v139
	s_waitcnt lgkmcnt(12)
	v_mfma_f32_32x32x16_bf16 v[64:79], v[130:133], v[96:99], v[64:79]
	v_add_f32_e32 v96, v211, v100
	v_add_f32_e32 v96, v214, v96
	v_add_f32_e32 v96, v212, v96
	v_add_f32_e32 v96, v215, v96
	v_add_f32_e32 v96, v216, v96
	v_add_f32_e32 v96, v219, v96
	v_add_f32_e32 v96, v146, v96
	s_waitcnt lgkmcnt(9)
	v_mfma_f32_32x32x16_bf16 v[80:95], v[164:167], v[112:115], v[80:95]
	v_add_f32_e32 v96, v147, v96
	v_add_f32_e32 v96, v144, v96
	v_add_f32_e32 v96, v145, v96
	v_add_f32_e32 v96, v140, v96
	v_add_f32_e32 v96, v118, v96
	v_add_f32_e32 v96, v119, v96
	v_add_f32_e32 v96, v136, v96
	v_mfma_f32_32x32x16_bf16 v[64:79], v[168:171], v[112:115], v[64:79]
	v_add_f32_e32 v96, v134, v96
	v_add_f32_e32 v96, v135, v96
	v_add_f32_e32 v96, v137, v96
	v_add_f32_e32 v96, v141, v96
	v_add_f32_e32 v96, v102, v96
	v_add_f32_e32 v96, v103, v96
	v_add_f32_e32 v96, v123, v96
	s_waitcnt lgkmcnt(6)
	v_mfma_f32_32x32x16_bf16 v[80:95], v[172:175], v[180:183], v[80:95]
	v_add_f32_e32 v96, v138, v96
	v_mov_b32_e32 v97, v96
	v_cvt_pk_bf16_f32 v98, v213, v217
	v_cvt_pk_bf16_f32 v99, v218, v220
	v_cvt_pk_bf16_f32 v100, v221, v223
	v_cvt_pk_bf16_f32 v101, v222, v224
	v_permlane32_swap_b32_e32 v96, v97
	v_mfma_f32_32x32x16_bf16 v[64:79], v[176:179], v[180:183], v[64:79]
	v_permlane32_swap_b32_e32 v98, v100
	v_permlane32_swap_b32_e32 v99, v101
	v_cvt_pk_bf16_f32 v112, v209, v210
	v_cvt_pk_bf16_f32 v113, v211, v214
	v_cvt_pk_bf16_f32 v114, v212, v215
	s_waitcnt lgkmcnt(3)
	v_mfma_f32_32x32x16_bf16 v[80:95], v[184:187], v[226:229], v[80:95]
	v_cvt_pk_bf16_f32 v115, v216, v219
	v_cvt_pk_bf16_f32 v118, v140, v118
	v_cvt_pk_bf16_f32 v119, v119, v136
	v_cvt_pk_bf16_f32 v120, v134, v135
	v_cvt_pk_bf16_f32 v121, v137, v141
	v_cvt_pk_bf16_f32 v122, v102, v103
	v_cvt_pk_bf16_f32 v123, v123, v138
	v_mfma_f32_32x32x16_bf16 v[64:79], v[188:191], v[226:229], v[64:79]
	v_permlane32_swap_b32_e32 v112, v114
	v_permlane32_swap_b32_e32 v113, v115
	v_permlane32_swap_b32_e32 v116, v118
	v_permlane32_swap_b32_e32 v117, v119
	s_waitcnt lgkmcnt(0)
; #define SBAR() __builtin_amdgcn_sched_barrier(0)
; __device__ __forceinline__ void partialSM(f32x16& p0, f32x16& p1, float& m_reg, float& mn, float& alpha) {
;   constexpr float C = ATT_SCALE * 1.4426950408889634f;
;   float pmax = p0[0];
; #pragma unroll
;   for (int r = 1; r < 16; ++r) pmax = fmaxf(pmax, p0[r]);
; #pragma unroll
;   for (int r = 0; r < 16; ++r) pmax = fmaxf(pmax, p1[r]);
;   { auto rr = __builtin_amdgcn_permlane32_swap(__float_as_uint(pmax), __float_as_uint(pmax), false, false);
;     pmax = fmaxf(__uint_as_float(rr[0]), __uint_as_float(rr[1])); }
;   if (__builtin_expect(__all(pmax - m_reg <= ATT_THR / ATT_SCALE), 1)) { mn = m_reg; alpha = 1.f; }
;   else { mn = fmaxf(m_reg, pmax); alpha = __builtin_amdgcn_exp2f((m_reg - mn) * C); m_reg = mn; }
; template <int D0> __device__ __forceinline__ void pv_one(f32x16& od, int vb, bf16x8 pa0, bf16x8 pa1, bf16x8 pa2, bf16x8 pa3) {
;   const s16x4 l0 = tr_read<v_rd_off(D0, 0, 0)>(vb), h0 = tr_read<v_rd_off(D0, 0, 1)>(vb), l1 = tr_read<v_rd_off(D0, 1, 0)>(vb), h1 = tr_read<v_rd_off(D0, 1, 1)>(vb);
;   const s16x4 l2 = tr_read<v_rd_off(D0, 2, 0)>(vb), h2 = tr_read<v_rd_off(D0, 2, 1)>(vb), l3 = tr_read<v_rd_off(D0, 3, 0)>(vb), h3 = tr_read<v_rd_off(D0, 3, 1)>(vb);
;   asm volatile("s_waitcnt lgkmcnt(0)" ::: "memory"); SBAR();
;     ...
;   od = __builtin_amdgcn_mfma_f32_32x32x16_bf16(pa0, PK(l0, h0), od, 0, 0, 0);
;   od = __builtin_amdgcn_mfma_f32_32x32x16_bf16(pa1, PK(l1, h1), od, 0, 0, 0);
;   od = __builtin_amdgcn_mfma_f32_32x32x16_bf16(pa2, PK(l2, h2), od, 0, 0, 0);
;   od = __builtin_amdgcn_mfma_f32_32x32x16_bf16(pa3, PK(l3, h3), od, 0, 0, 0);
;     ...
; }
; __device__ __forceinline__ void pv_d0(f32x16* o, int vb, bf16x8 pa0, bf16x8 pa1, bf16x8 pa2, bf16x8 pa3) {
;   pv_one<0>(o[0], vb, pa0, pa1, pa2, pa3); pv_one<1>(o[1], vb, pa0, pa1, pa2, pa3); pv_one<2>(o[2], vb, pa0, pa1, pa2, pa3); pv_one<3>(o[3], vb, pa0, pa1, pa2, pa3);
	v_mfma_f32_32x32x16_bf16 v[80:95], v[196:199], v[108:111], v[80:95]
	v_permlane32_swap_b32_e32 v120, v122
	v_permlane32_swap_b32_e32 v121, v123
	v_mfma_f32_32x32x16_bf16 v[64:79], v[104:107], v[108:111], v[64:79]
	ds_read_b64_tr_b16 v[102:103], v163 offset:0
	ds_read_b64_tr_b16 v[104:105], v163 offset:0x800
	ds_read_b64_tr_b16 v[106:107], v163 offset:0x1000
	ds_read_b64_tr_b16 v[108:109], v163 offset:0x1800
	ds_read_b64_tr_b16 v[124:125], v163 offset:0x2000
	ds_read_b64_tr_b16 v[126:127], v163 offset:0x2800
	ds_read_b64_tr_b16 v[130:131], v163 offset:0x3000
	ds_read_b64_tr_b16 v[132:133], v163 offset:0x3800
	s_waitcnt lgkmcnt(0)
	s_nop 0
	v_mfma_f32_32x32x16_bf16 v[48:63], v[98:101], v[102:105], v[48:63]
	ds_read_b64_tr_b16 v[102:103], v163 offset:0x200
	ds_read_b64_tr_b16 v[104:105], v163 offset:0xa00
	v_mfma_f32_32x32x16_bf16 v[48:63], v[112:115], v[106:109], v[48:63]
	ds_read_b64_tr_b16 v[106:107], v163 offset:0x1200
	ds_read_b64_tr_b16 v[108:109], v163 offset:0x1a00
	v_mfma_f32_32x32x16_bf16 v[48:63], v[116:119], v[124:127], v[48:63]
	ds_read_b64_tr_b16 v[124:125], v163 offset:0x2200
	ds_read_b64_tr_b16 v[126:127], v163 offset:0x2a00
	ds_read_b64_tr_b16 v[134:135], v163 offset:0x3200
	ds_read_b64_tr_b16 v[136:137], v163 offset:0x3a00
	s_waitcnt lgkmcnt(0)
	v_mfma_f32_32x32x16_bf16 v[48:63], v[120:123], v[130:133], v[48:63]
	v_mfma_f32_32x32x16_bf16 v[32:47], v[98:101], v[102:105], v[32:47]
	ds_read_b64_tr_b16 v[102:103], v163 offset:0x400
	ds_read_b64_tr_b16 v[104:105], v163 offset:0xc00
	v_mfma_f32_32x32x16_bf16 v[32:47], v[112:115], v[106:109], v[32:47]
	ds_read_b64_tr_b16 v[106:107], v163 offset:0x1400
	ds_read_b64_tr_b16 v[108:109], v163 offset:0x1c00
	v_mfma_f32_32x32x16_bf16 v[32:47], v[116:119], v[124:127], v[32:47]
	ds_read_b64_tr_b16 v[124:125], v163 offset:0x2400
	ds_read_b64_tr_b16 v[126:127], v163 offset:0x2c00
	ds_read_b64_tr_b16 v[130:131], v163 offset:0x3400
	ds_read_b64_tr_b16 v[132:133], v163 offset:0x3c00
	s_waitcnt lgkmcnt(0)
	v_mfma_f32_32x32x16_bf16 v[32:47], v[120:123], v[134:137], v[32:47]
	v_mfma_f32_32x32x16_bf16 v[16:31], v[98:101], v[102:105], v[16:31]
	ds_read_b64_tr_b16 v[102:103], v163 offset:0x600
	ds_read_b64_tr_b16 v[104:105], v163 offset:0xe00
	v_mfma_f32_32x32x16_bf16 v[16:31], v[112:115], v[106:109], v[16:31]
	ds_read_b64_tr_b16 v[106:107], v163 offset:0x1600
	ds_read_b64_tr_b16 v[108:109], v163 offset:0x1e00
	v_mfma_f32_32x32x16_bf16 v[16:31], v[116:119], v[124:127], v[16:31]
	ds_read_b64_tr_b16 v[124:125], v163 offset:0x2600
	ds_read_b64_tr_b16 v[126:127], v163 offset:0x2e00
	ds_read_b64_tr_b16 v[134:135], v163 offset:0x3600
	ds_read_b64_tr_b16 v[136:137], v163 offset:0x3e00
	s_waitcnt lgkmcnt(0)
	v_mfma_f32_32x32x16_bf16 v[16:31], v[120:123], v[130:133], v[16:31]
	v_mfma_f32_32x32x16_bf16 v[0:15], v[98:101], v[102:105], v[0:15]
	v_max_f32_e32 v110, v81, v81
	v_max_f32_e32 v111, v80, v80
	v_max_f32_e32 v110, v111, v110
	v_max3_f32 v110, v110, v82, v83
	v_max3_f32 v110, v110, v84, v85
	v_max3_f32 v98, v110, v86, v87
	v_max3_f32 v98, v98, v88, v89
	v_max3_f32 v98, v98, v90, v91
	v_mfma_f32_32x32x16_bf16 v[0:15], v[112:115], v[106:109], v[0:15]
	v_max3_f32 v98, v98, v92, v93
	v_max3_f32 v98, v98, v94, v95
	v_max3_f32 v98, v98, v64, v65
	v_max3_f32 v98, v98, v66, v67
	v_max3_f32 v98, v98, v68, v69
	v_max3_f32 v98, v98, v70, v71
	v_max3_f32 v98, v98, v72, v73
	v_max3_f32 v98, v98, v74, v75
	v_mfma_f32_32x32x16_bf16 v[0:15], v[116:119], v[124:127], v[0:15]
	v_max3_f32 v98, v98, v76, v77
	v_max3_f32 v98, v98, v78, v79
	v_mov_b32_e32 v99, v98
	s_nop 1
	v_permlane32_swap_b32_e32 v98, v99
	v_max_f32_e32 v99, v99, v99
	v_max_f32_e32 v98, v98, v98
	v_max_f32_e32 v98, v98, v99
	v_max_f32_e32 v99, v195, v195
	v_max_f32_e32 v99, v99, v98
	v_sub_f32_e32 v100, v98, v195
	v_mfma_f32_32x32x16_bf16 v[0:15], v[120:123], v[134:137], v[0:15]
	v_sub_f32_e32 v98, v195, v99
	v_mul_f32_e32 v98, 0x3dd53b94, v98
	v_exp_f32_e32 v98, v98
	v_cmp_ge_f32_e32 vcc, s69, v100
	s_cmp_eq_u64 vcc, exec
	s_cselect_b64 s[8:9], -1, 0
	v_cndmask_b32_e64 v98, v98, 1.0, s[8:9]
	v_cmp_gt_f32_e32 vcc, 1.0, v98
	s_waitcnt vmcnt(0)
	s_barrier
	s_cbranch_vccz .LBB0_367
	s_and_saveexec_b64 s[10:11], s[6:7]
	ds_write_b32 v160, v98 offset:128
	s_or_b64 exec, exec, s[10:11]
	s_waitcnt lgkmcnt(0)
	v_add_u32_e32 v112, v253, v128
	ds_read_b128 v[100:103], v112 offset:224
	ds_read_b128 v[104:107], v112 offset:192
	ds_read_b128 v[108:111], v112 offset:160
	ds_read_b128 v[112:115], v112 offset:128
	s_waitcnt lgkmcnt(3)
	v_pk_mul_f32 v[60:61], v[60:61], v[100:101]
	s_waitcnt lgkmcnt(2)
	v_pk_mul_f32 v[56:57], v[56:57], v[104:105]
	s_waitcnt lgkmcnt(1)
	v_pk_mul_f32 v[52:53], v[52:53], v[108:109]
	v_pk_mul_f32 v[62:63], v[62:63], v[102:103]
	v_pk_mul_f32 v[58:59], v[58:59], v[106:107]
	v_pk_mul_f32 v[54:55], v[54:55], v[110:111]
	s_waitcnt lgkmcnt(0)
	v_pk_mul_f32 v[50:51], v[50:51], v[114:115]
	v_pk_mul_f32 v[48:49], v[48:49], v[112:113]
	v_pk_mul_f32 v[44:45], v[44:45], v[100:101]
	v_pk_mul_f32 v[40:41], v[40:41], v[104:105]
	v_pk_mul_f32 v[36:37], v[36:37], v[108:109]
	v_pk_mul_f32 v[46:47], v[46:47], v[102:103]
	v_pk_mul_f32 v[42:43], v[42:43], v[106:107]
	v_pk_mul_f32 v[38:39], v[38:39], v[110:111]
	v_pk_mul_f32 v[34:35], v[34:35], v[114:115]
	v_pk_mul_f32 v[32:33], v[32:33], v[112:113]
	v_pk_mul_f32 v[28:29], v[28:29], v[100:101]
	v_pk_mul_f32 v[24:25], v[24:25], v[104:105]
	v_pk_mul_f32 v[20:21], v[20:21], v[108:109]
	v_pk_mul_f32 v[30:31], v[30:31], v[102:103]
	v_pk_mul_f32 v[26:27], v[26:27], v[106:107]
	v_pk_mul_f32 v[22:23], v[22:23], v[110:111]
	v_pk_mul_f32 v[18:19], v[18:19], v[114:115]
	v_pk_mul_f32 v[16:17], v[16:17], v[112:113]
	v_pk_mul_f32 v[12:13], v[12:13], v[100:101]
	v_pk_mul_f32 v[8:9], v[8:9], v[104:105]
	v_pk_mul_f32 v[4:5], v[4:5], v[108:109]
	v_pk_mul_f32 v[14:15], v[14:15], v[102:103]
	v_pk_mul_f32 v[10:11], v[10:11], v[106:107]
	v_pk_mul_f32 v[6:7], v[6:7], v[110:111]
	v_pk_mul_f32 v[2:3], v[2:3], v[114:115]
	v_pk_mul_f32 v[0:1], v[0:1], v[112:113]
